# QKPREP: nt (streaming) hint on the f32 context K/V output stores, which go to the output tensor and are never re-read; same code size
# speedup vs baseline: 1.0096x; 1.0039x over previous
.LBB0_763:
	s_mul_i32 s51, s19, s4
	s_add_i32 s52, s51, s9
	s_ashr_i32 s53, s52, 31
	s_and_b32 s23, s13, 0xff
	s_lshl_b64 s[52:53], s[52:53], 8
	s_or_b32 s23, s52, s23
	s_mul_i32 s51, s53, s18
	s_mul_hi_u32 s52, s23, s18
	s_add_i32 s53, s52, s51
	s_mul_i32 s52, s23, s18
	v_lshl_add_u64 v[50:51], s[52:53], 2, v[40:41]
	global_store_dwordx4 v[50:51], v[30:33], off nt
	global_store_dwordx4 v[50:51], v[26:29], off offset:16 nt
	global_store_dwordx4 v[50:51], v[22:25], off offset:32 nt
	global_store_dwordx4 v[50:51], v[18:21], off offset:48 nt
	global_store_dwordx4 v[50:51], v[14:17], off offset:64 nt
	global_store_dwordx4 v[50:51], v[10:13], off offset:80 nt
	global_store_dwordx4 v[50:51], v[6:9], off offset:96 nt
	global_store_dwordx4 v[50:51], v[2:5], off offset:112 nt
	s_or_b64 exec, exec, s[16:17]
	s_and_saveexec_b64 s[16:17], s[44:45]
	s_xor_b64 s[16:17], exec, s[16:17]
	s_cbranch_execnz .LBB0_761

.LBB0_766:
	s_or_b64 exec, exec, s[38:39]
	s_andn2_b64 vcc, exec, s[36:37]
	s_cbranch_vccnz .LBB0_756
	s_mul_i32 s16, s19, s4
	s_add_i32 s16, s16, s9
	s_ashr_i32 s17, s16, 31
	s_and_b32 s23, s12, 0xff
	s_lshl_b64 s[16:17], s[16:17], 8
	s_or_b32 s16, s16, s23
	v_mov_b32_e32 v2, s16
	s_mul_i32 s19, s11, s17
	v_mad_u64_u32 v[2:3], s[16:17], s11, v2, v[44:45]
	v_add_u32_e32 v3, s19, v3
	v_lshlrev_b32_e32 v8, 16, v142
	v_and_b32_e32 v9, 0xffff0000, v142
	v_lshlrev_b32_e32 v10, 16, v143
	v_and_b32_e32 v11, 0xffff0000, v143
	global_store_dwordx4 v[2:3], v[8:11], off nt
	s_cmpk_lt_u32 s1, 0x400
	s_cbranch_scc1 .LBB0_756
	v_lshlrev_b32_e32 v12, 16, v144
	v_and_b32_e32 v13, 0xffff0000, v144
	v_lshlrev_b32_e32 v14, 16, v145
	v_and_b32_e32 v15, 0xffff0000, v145
	global_store_dwordx4 v[2:3], v[12:15], off offset:1024 nt
	v_lshlrev_b32_e32 v16, 16, v146
	v_and_b32_e32 v17, 0xffff0000, v146
	v_lshlrev_b32_e32 v18, 16, v147
	v_and_b32_e32 v19, 0xffff0000, v147
	global_store_dwordx4 v[2:3], v[16:19], off offset:2048 nt
	v_lshlrev_b32_e32 v20, 16, v148
	v_and_b32_e32 v21, 0xffff0000, v148
	v_lshlrev_b32_e32 v22, 16, v149
	v_and_b32_e32 v23, 0xffff0000, v149
	global_store_dwordx4 v[2:3], v[20:23], off offset:3072 nt
	s_branch .LBB0_756
